# baseline (speedup 1.0000x reference)
; #define PHASE_P(name) KParams* name##_ptr = (KParams*)__builtin_amdgcn_kernarg_segment_ptr(); asm volatile("" : "+s"(name##_ptr)); KParams& name = *name##_ptr
; #define PH(n) for (int rep_ = 0, nrep_ = 1 + (int)((repm >> (n)) & 1u); rep_ < nrep_; ++rep_)
; __device__ __forceinline__ void dsa_tile(const Params& p, unsigned char* smem, int tile) {
;     ...
;     __syncthreads();
; }
; __global__ void __launch_bounds__(NTHREADS, 2) fwd_megakernel(ParamsT p_unused) {
;     ...
;     PH(6) { PHASE_P(p); for (int t = blockIdx.x; t < 2048; t += G) dsa_tile(p, smem, t); }
.LBB0_284:
	s_setprio 0
	s_add_i32 s94, s94, s44
	s_cmpk_gt_i32 s94, 0x7ff
	s_barrier
	s_cbranch_scc1 .LBB0_281

; __device__ __forceinline__ void dsa_tile(const Params& p, unsigned char* smem, int tile) {
;     ...
;     for (int qi = wid * 2; qi < wid * 2 + 2; ++qi) {
;         int lane_o = threadIdx.x & 63; asm volatile("" : "+v"(lane_o));
;         const int lane = lane_o, fr = lane & 15, fq = lane >> 4;
;         const int t = q0 + qi;
;         int nsel;
;         if (t < 256) {
.LBB0_292:
	s_setprio 0
	s_cmp_lt_u32 s58, 8
	s_cbranch_scc1 .Ltopk_prio_done
	s_bitcmp0_b32 s58, 0
	s_cbranch_scc0 .Ltopk_prio_done
	s_setprio 1
